# v35 plus: 64-bit accumulator zeroing at GEMM unit start, context-row split-K partial loads issued up front in the mixer adaLN phase too
# speedup vs baseline: 1.0249x; 1.0054x over previous
.LBB0_119:
	v_lshlrev_b64 v[38:39], 1, v[38:39]
	v_lshl_add_u64 v[40:41], s[18:19], 0, v[38:39]
	v_lshl_add_u64 v[42:43], s[22:23], 0, v[38:39]
	v_lshl_add_u64 v[44:45], s[24:25], 0, v[38:39]
	v_lshl_add_u64 v[46:47], s[6:7], 0, v[38:39]
	global_load_dwordx2 v[134:135], v[40:41], off
	global_load_dwordx2 v[136:137], v[42:43], off
	global_load_dwordx2 v[138:139], v[44:45], off
	global_load_dwordx2 v[140:141], v[46:47], off
	global_load_dwordx2 v[142:143], v[40:41], off offset:512
	global_load_dwordx2 v[144:145], v[42:43], off offset:512
	global_load_dwordx2 v[146:147], v[44:45], off offset:512
	global_load_dwordx2 v[148:149], v[46:47], off offset:512
	global_load_dwordx2 v[150:151], v[40:41], off offset:1024
	global_load_dwordx2 v[156:157], v[42:43], off offset:1024
	global_load_dwordx2 v[158:159], v[44:45], off offset:1024
	global_load_dwordx2 v[160:161], v[46:47], off offset:1024
	global_load_dwordx2 v[162:163], v[40:41], off offset:1536
	global_load_dwordx2 v[164:165], v[42:43], off offset:1536
	global_load_dwordx2 v[166:167], v[44:45], off offset:1536
	global_load_dwordx2 v[168:169], v[46:47], off offset:1536
	v_lshl_add_u64 v[38:39], s[12:13], 0, v[38:39]
	s_waitcnt vmcnt(15)
	v_cvt_f32_f16_e32 v64, v134
	v_cvt_f32_f16_sdwa v65, v134 dst_sel:DWORD dst_unused:UNUSED_PAD src0_sel:WORD_1
	v_cvt_f32_f16_e32 v48, v135
	v_cvt_f32_f16_sdwa v49, v135 dst_sel:DWORD dst_unused:UNUSED_PAD src0_sel:WORD_1
	s_waitcnt vmcnt(14)
	v_cvt_f32_f16_e32 v66, v136
	v_cvt_f32_f16_sdwa v67, v136 dst_sel:DWORD dst_unused:UNUSED_PAD src0_sel:WORD_1
	v_cvt_f32_f16_e32 v50, v137
	v_cvt_f32_f16_sdwa v51, v137 dst_sel:DWORD dst_unused:UNUSED_PAD src0_sel:WORD_1
	s_waitcnt vmcnt(13)
	v_cvt_f32_f16_e32 v68, v138
	v_cvt_f32_f16_sdwa v69, v138 dst_sel:DWORD dst_unused:UNUSED_PAD src0_sel:WORD_1
	v_cvt_f32_f16_e32 v60, v139
	v_cvt_f32_f16_sdwa v61, v139 dst_sel:DWORD dst_unused:UNUSED_PAD src0_sel:WORD_1
	s_waitcnt vmcnt(12)
	v_cvt_f32_f16_e32 v70, v140
	v_cvt_f32_f16_sdwa v71, v140 dst_sel:DWORD dst_unused:UNUSED_PAD src0_sel:WORD_1
	v_cvt_f32_f16_e32 v62, v141
	v_cvt_f32_f16_sdwa v63, v141 dst_sel:DWORD dst_unused:UNUSED_PAD src0_sel:WORD_1
	v_pk_add_f32 v[64:65], v[64:65], v[66:67]
	v_pk_add_f32 v[48:49], v[48:49], v[50:51]
	v_pk_add_f32 v[50:51], v[68:69], v[70:71]
	v_pk_add_f32 v[60:61], v[60:61], v[62:63]
	v_pk_add_f32 v[50:51], v[64:65], v[50:51]
	v_pk_add_f32 v[48:49], v[48:49], v[60:61]
	v_pk_add_f32 v[30:31], v[30:31], v[50:51]
	v_pk_add_f32 v[32:33], v[32:33], v[48:49]
	v_cvt_pk_f16_f32 v48, v30, v31
	v_cvt_pk_f16_f32 v49, v32, v33
	global_store_dwordx2 v[38:39], v[48:49], off
	s_waitcnt vmcnt(12)
	v_cvt_f32_f16_e32 v64, v142
	v_cvt_f32_f16_sdwa v65, v142 dst_sel:DWORD dst_unused:UNUSED_PAD src0_sel:WORD_1
	v_cvt_f32_f16_e32 v48, v143
	v_cvt_f32_f16_sdwa v49, v143 dst_sel:DWORD dst_unused:UNUSED_PAD src0_sel:WORD_1
	s_waitcnt vmcnt(11)
	v_cvt_f32_f16_e32 v66, v144
	v_cvt_f32_f16_sdwa v67, v144 dst_sel:DWORD dst_unused:UNUSED_PAD src0_sel:WORD_1
	v_cvt_f32_f16_e32 v50, v145
	v_cvt_f32_f16_sdwa v51, v145 dst_sel:DWORD dst_unused:UNUSED_PAD src0_sel:WORD_1
	s_waitcnt vmcnt(10)
	v_cvt_f32_f16_e32 v68, v146
	v_cvt_f32_f16_sdwa v69, v146 dst_sel:DWORD dst_unused:UNUSED_PAD src0_sel:WORD_1
	v_cvt_f32_f16_e32 v60, v147
	v_cvt_f32_f16_sdwa v61, v147 dst_sel:DWORD dst_unused:UNUSED_PAD src0_sel:WORD_1
	s_waitcnt vmcnt(9)
	v_cvt_f32_f16_e32 v70, v148
	v_cvt_f32_f16_sdwa v71, v148 dst_sel:DWORD dst_unused:UNUSED_PAD src0_sel:WORD_1
	v_cvt_f32_f16_e32 v62, v149
	v_cvt_f32_f16_sdwa v63, v149 dst_sel:DWORD dst_unused:UNUSED_PAD src0_sel:WORD_1
	v_pk_add_f32 v[64:65], v[64:65], v[66:67]
	v_pk_add_f32 v[48:49], v[48:49], v[50:51]
	v_pk_add_f32 v[50:51], v[68:69], v[70:71]
	v_pk_add_f32 v[60:61], v[60:61], v[62:63]
	v_pk_add_f32 v[50:51], v[64:65], v[50:51]
	v_pk_add_f32 v[48:49], v[48:49], v[60:61]
	v_pk_add_f32 v[26:27], v[26:27], v[50:51]
	v_pk_add_f32 v[28:29], v[28:29], v[48:49]
	v_cvt_pk_f16_f32 v48, v26, v27
	v_cvt_pk_f16_f32 v49, v28, v29
	global_store_dwordx2 v[38:39], v[48:49], off offset:512
	s_waitcnt vmcnt(9)
	v_cvt_f32_f16_e32 v64, v150
	v_cvt_f32_f16_sdwa v65, v150 dst_sel:DWORD dst_unused:UNUSED_PAD src0_sel:WORD_1
	v_cvt_f32_f16_e32 v48, v151
	v_cvt_f32_f16_sdwa v49, v151 dst_sel:DWORD dst_unused:UNUSED_PAD src0_sel:WORD_1
	s_waitcnt vmcnt(8)
	v_cvt_f32_f16_e32 v66, v156
	v_cvt_f32_f16_sdwa v67, v156 dst_sel:DWORD dst_unused:UNUSED_PAD src0_sel:WORD_1
	v_cvt_f32_f16_e32 v50, v157
	v_cvt_f32_f16_sdwa v51, v157 dst_sel:DWORD dst_unused:UNUSED_PAD src0_sel:WORD_1
	s_waitcnt vmcnt(7)
	v_cvt_f32_f16_e32 v68, v158
	v_cvt_f32_f16_sdwa v69, v158 dst_sel:DWORD dst_unused:UNUSED_PAD src0_sel:WORD_1
	v_cvt_f32_f16_e32 v60, v159
	v_cvt_f32_f16_sdwa v61, v159 dst_sel:DWORD dst_unused:UNUSED_PAD src0_sel:WORD_1
	s_waitcnt vmcnt(6)
	v_cvt_f32_f16_e32 v70, v160
	v_cvt_f32_f16_sdwa v71, v160 dst_sel:DWORD dst_unused:UNUSED_PAD src0_sel:WORD_1
	v_cvt_f32_f16_e32 v62, v161
	v_cvt_f32_f16_sdwa v63, v161 dst_sel:DWORD dst_unused:UNUSED_PAD src0_sel:WORD_1
	v_pk_add_f32 v[64:65], v[64:65], v[66:67]
	v_pk_add_f32 v[48:49], v[48:49], v[50:51]
	v_pk_add_f32 v[50:51], v[68:69], v[70:71]
	v_pk_add_f32 v[60:61], v[60:61], v[62:63]
	v_pk_add_f32 v[50:51], v[64:65], v[50:51]
	v_pk_add_f32 v[48:49], v[48:49], v[60:61]
	v_pk_add_f32 v[22:23], v[22:23], v[50:51]
	v_pk_add_f32 v[24:25], v[24:25], v[48:49]
	v_cvt_pk_f16_f32 v48, v22, v23
	v_cvt_pk_f16_f32 v49, v24, v25
	global_store_dwordx2 v[38:39], v[48:49], off offset:1024
	s_waitcnt vmcnt(6)
	v_cvt_f32_f16_e32 v64, v162
	v_cvt_f32_f16_sdwa v65, v162 dst_sel:DWORD dst_unused:UNUSED_PAD src0_sel:WORD_1
	v_cvt_f32_f16_e32 v48, v163
	v_cvt_f32_f16_sdwa v49, v163 dst_sel:DWORD dst_unused:UNUSED_PAD src0_sel:WORD_1
	s_waitcnt vmcnt(5)
	v_cvt_f32_f16_e32 v66, v164
	v_cvt_f32_f16_sdwa v67, v164 dst_sel:DWORD dst_unused:UNUSED_PAD src0_sel:WORD_1
	v_cvt_f32_f16_e32 v50, v165
	v_cvt_f32_f16_sdwa v51, v165 dst_sel:DWORD dst_unused:UNUSED_PAD src0_sel:WORD_1
	s_waitcnt vmcnt(4)
	v_cvt_f32_f16_e32 v68, v166
	v_cvt_f32_f16_sdwa v69, v166 dst_sel:DWORD dst_unused:UNUSED_PAD src0_sel:WORD_1
	v_cvt_f32_f16_e32 v60, v167
	v_cvt_f32_f16_sdwa v61, v167 dst_sel:DWORD dst_unused:UNUSED_PAD src0_sel:WORD_1
	s_waitcnt vmcnt(3)
	v_cvt_f32_f16_e32 v70, v168
	v_cvt_f32_f16_sdwa v71, v168 dst_sel:DWORD dst_unused:UNUSED_PAD src0_sel:WORD_1
	v_cvt_f32_f16_e32 v62, v169
	v_cvt_f32_f16_sdwa v63, v169 dst_sel:DWORD dst_unused:UNUSED_PAD src0_sel:WORD_1
	v_pk_add_f32 v[64:65], v[64:65], v[66:67]
	v_pk_add_f32 v[48:49], v[48:49], v[50:51]
	v_pk_add_f32 v[50:51], v[68:69], v[70:71]
	v_pk_add_f32 v[60:61], v[60:61], v[62:63]
	v_pk_add_f32 v[50:51], v[64:65], v[50:51]
	v_pk_add_f32 v[48:49], v[48:49], v[60:61]
	v_pk_add_f32 v[18:19], v[18:19], v[50:51]
	v_pk_add_f32 v[20:21], v[20:21], v[48:49]
	v_cvt_pk_f16_f32 v48, v18, v19
	v_cvt_pk_f16_f32 v49, v20, v21
	global_store_dwordx2 v[38:39], v[48:49], off offset:1536
	s_branch .LBB0_113

.LBB0_181:
	s_ashr_i32 s39, s38, 31
	s_lshl_b64 s[22:23], s[38:39], 19
	s_add_u32 s22, s12, s22
	s_addc_u32 s23, s13, s23
	s_and_b64 s[24:25], s[2:3], exec
	s_cselect_b32 s39, s23, s5
	s_cselect_b32 s49, s22, s4
	s_ashr_i32 s15, s14, 31
	s_lshl_b64 s[24:25], s[14:15], 19
	s_add_u32 s24, s20, s24
	s_addc_u32 s25, s28, s25
	s_and_b64 s[26:27], s[2:3], exec
	s_cselect_b32 s15, s25, s7
	s_cselect_b32 s50, s24, s6
	s_add_u32 s4, s4, 0x40080
	s_addc_u32 s5, s5, 0
	s_add_u32 s51, s6, 0x100
	v_mov_b32_e32 v2, 0
	s_addc_u32 s52, s7, 0
	s_mov_b32 s53, -2
	v_mov_b64_e32 v[2:3], 0
	v_mov_b64_e32 v[4:5], 0
	v_mov_b64_e32 v[6:7], 0
	v_mov_b64_e32 v[8:9], 0
	v_mov_b64_e32 v[10:11], 0
	v_mov_b64_e32 v[12:13], 0
	v_mov_b64_e32 v[14:15], 0
	v_mov_b64_e32 v[16:17], 0
	v_mov_b64_e32 v[18:19], 0
	v_mov_b64_e32 v[20:21], 0
	v_mov_b64_e32 v[22:23], 0
	v_mov_b64_e32 v[24:25], 0
	v_mov_b64_e32 v[26:27], 0
	v_mov_b64_e32 v[28:29], 0
	v_mov_b64_e32 v[30:31], 0
	v_mov_b64_e32 v[32:33], 0
	v_mov_b64_e32 v[34:35], 0
	v_mov_b64_e32 v[36:37], 0
	v_mov_b64_e32 v[38:39], 0
	v_mov_b64_e32 v[40:41], 0
	v_mov_b64_e32 v[42:43], 0
	v_mov_b64_e32 v[44:45], 0
	v_mov_b64_e32 v[46:47], 0
	v_mov_b64_e32 v[48:49], 0
	v_mov_b64_e32 v[50:51], 0
	v_mov_b64_e32 v[52:53], 0
	v_mov_b64_e32 v[54:55], 0
	v_mov_b64_e32 v[56:57], 0
	v_mov_b64_e32 v[58:59], 0
	v_mov_b64_e32 v[60:61], 0
	v_mov_b64_e32 v[62:63], 0
	v_mov_b64_e32 v[64:65], 0
	v_mov_b64_e32 v[66:67], 0
	v_mov_b64_e32 v[68:69], 0
	v_mov_b64_e32 v[70:71], 0
	v_mov_b64_e32 v[72:73], 0
	v_mov_b64_e32 v[74:75], 0
	v_mov_b64_e32 v[76:77], 0
	v_mov_b64_e32 v[78:79], 0
	v_mov_b64_e32 v[80:81], 0
	v_mov_b64_e32 v[82:83], 0
	v_mov_b64_e32 v[84:85], 0
	v_mov_b64_e32 v[86:87], 0
	v_mov_b64_e32 v[88:89], 0
	v_mov_b64_e32 v[90:91], 0
	v_mov_b64_e32 v[92:93], 0
	v_mov_b64_e32 v[94:95], 0
	v_mov_b64_e32 v[96:97], 0
	v_mov_b64_e32 v[98:99], 0
	v_mov_b64_e32 v[100:101], 0
	v_mov_b64_e32 v[102:103], 0
	v_mov_b64_e32 v[104:105], 0
	v_mov_b64_e32 v[106:107], 0
	v_mov_b64_e32 v[108:109], 0
	v_mov_b64_e32 v[110:111], 0
	v_mov_b64_e32 v[112:113], 0
	v_mov_b64_e32 v[114:115], 0
	v_mov_b64_e32 v[116:117], 0
	v_mov_b64_e32 v[118:119], 0
	v_mov_b64_e32 v[120:121], 0
	v_mov_b64_e32 v[122:123], 0
	v_mov_b64_e32 v[124:125], 0
	v_mov_b64_e32 v[126:127], 0
	v_mov_b64_e32 v[128:129], 0
	.p2align 6

.LBB0_219:
	s_ashr_i32 s19, s18, 31
	s_lshl_b64 s[22:23], s[18:19], 19
	s_add_u32 s22, s4, s22
	s_addc_u32 s23, s5, s23
	s_and_b64 s[24:25], s[2:3], exec
	s_cselect_b32 s19, s23, s37
	s_cselect_b32 s49, s22, s36
	s_ashr_i32 s17, s16, 31
	s_lshl_b64 s[24:25], s[16:17], 19
	s_add_u32 s24, s20, s24
	s_addc_u32 s25, s28, s25
	s_and_b64 s[38:39], s[2:3], exec
	s_cselect_b32 s17, s25, s27
	s_cselect_b32 s50, s24, s26
	s_add_u32 s36, s36, 0x40080
	s_addc_u32 s37, s37, 0
	s_add_u32 s51, s26, 0x100
	v_mov_b32_e32 v2, 0
	s_addc_u32 s52, s27, 0
	s_mov_b32 s53, -2
	v_mov_b64_e32 v[2:3], 0
	v_mov_b64_e32 v[4:5], 0
	v_mov_b64_e32 v[6:7], 0
	v_mov_b64_e32 v[8:9], 0
	v_mov_b64_e32 v[10:11], 0
	v_mov_b64_e32 v[12:13], 0
	v_mov_b64_e32 v[14:15], 0
	v_mov_b64_e32 v[16:17], 0
	v_mov_b64_e32 v[18:19], 0
	v_mov_b64_e32 v[20:21], 0
	v_mov_b64_e32 v[22:23], 0
	v_mov_b64_e32 v[24:25], 0
	v_mov_b64_e32 v[26:27], 0
	v_mov_b64_e32 v[28:29], 0
	v_mov_b64_e32 v[30:31], 0
	v_mov_b64_e32 v[32:33], 0
	v_mov_b64_e32 v[34:35], 0
	v_mov_b64_e32 v[36:37], 0
	v_mov_b64_e32 v[38:39], 0
	v_mov_b64_e32 v[40:41], 0
	v_mov_b64_e32 v[42:43], 0
	v_mov_b64_e32 v[44:45], 0
	v_mov_b64_e32 v[46:47], 0
	v_mov_b64_e32 v[48:49], 0
	v_mov_b64_e32 v[50:51], 0
	v_mov_b64_e32 v[52:53], 0
	v_mov_b64_e32 v[54:55], 0
	v_mov_b64_e32 v[56:57], 0
	v_mov_b64_e32 v[58:59], 0
	v_mov_b64_e32 v[60:61], 0
	v_mov_b64_e32 v[62:63], 0
	v_mov_b64_e32 v[64:65], 0
	v_mov_b64_e32 v[66:67], 0
	v_mov_b64_e32 v[68:69], 0
	v_mov_b64_e32 v[70:71], 0
	v_mov_b64_e32 v[72:73], 0
	v_mov_b64_e32 v[74:75], 0
	v_mov_b64_e32 v[76:77], 0
	v_mov_b64_e32 v[78:79], 0
	v_mov_b64_e32 v[80:81], 0
	v_mov_b64_e32 v[82:83], 0
	v_mov_b64_e32 v[84:85], 0
	v_mov_b64_e32 v[86:87], 0
	v_mov_b64_e32 v[88:89], 0
	v_mov_b64_e32 v[90:91], 0
	v_mov_b64_e32 v[92:93], 0
	v_mov_b64_e32 v[94:95], 0
	v_mov_b64_e32 v[96:97], 0
	v_mov_b64_e32 v[98:99], 0
	v_mov_b64_e32 v[100:101], 0
	v_mov_b64_e32 v[102:103], 0
	v_mov_b64_e32 v[104:105], 0
	v_mov_b64_e32 v[106:107], 0
	v_mov_b64_e32 v[108:109], 0
	v_mov_b64_e32 v[110:111], 0
	v_mov_b64_e32 v[112:113], 0
	v_mov_b64_e32 v[114:115], 0
	v_mov_b64_e32 v[116:117], 0
	v_mov_b64_e32 v[118:119], 0
	v_mov_b64_e32 v[120:121], 0
	v_mov_b64_e32 v[122:123], 0
	v_mov_b64_e32 v[124:125], 0
	v_mov_b64_e32 v[126:127], 0
	v_mov_b64_e32 v[128:129], 0
	.p2align 6

.LBB0_375:
	s_ashr_i32 s23, s22, 31
	s_lshl_b64 s[26:27], s[22:23], 17
	s_add_u32 s36, s29, s26
	s_addc_u32 s37, s40, s27
	s_and_b64 s[4:5], s[4:5], exec
	v_mov_b32_e32 v2, 0
	s_cselect_b32 s23, s37, s17
	s_cselect_b32 s52, s36, s16
	s_mov_b32 s9, 0
	s_mov_b64 s[4:5], -1
	s_mov_b64 s[38:39], 0
	v_mov_b64_e32 v[2:3], 0
	v_mov_b64_e32 v[4:5], 0
	v_mov_b64_e32 v[6:7], 0
	v_mov_b64_e32 v[8:9], 0
	v_mov_b64_e32 v[10:11], 0
	v_mov_b64_e32 v[12:13], 0
	v_mov_b64_e32 v[14:15], 0
	v_mov_b64_e32 v[16:17], 0
	v_mov_b64_e32 v[18:19], 0
	v_mov_b64_e32 v[20:21], 0
	v_mov_b64_e32 v[22:23], 0
	v_mov_b64_e32 v[24:25], 0
	v_mov_b64_e32 v[26:27], 0
	v_mov_b64_e32 v[28:29], 0
	v_mov_b64_e32 v[30:31], 0
	v_mov_b64_e32 v[32:33], 0
	v_mov_b64_e32 v[34:35], 0
	v_mov_b64_e32 v[36:37], 0
	v_mov_b64_e32 v[38:39], 0
	v_mov_b64_e32 v[40:41], 0
	v_mov_b64_e32 v[42:43], 0
	v_mov_b64_e32 v[44:45], 0
	v_mov_b64_e32 v[46:47], 0
	v_mov_b64_e32 v[48:49], 0
	v_mov_b64_e32 v[50:51], 0
	v_mov_b64_e32 v[52:53], 0
	v_mov_b64_e32 v[54:55], 0
	v_mov_b64_e32 v[56:57], 0
	v_mov_b64_e32 v[58:59], 0
	v_mov_b64_e32 v[60:61], 0
	v_mov_b64_e32 v[62:63], 0
	v_mov_b64_e32 v[64:65], 0
	v_mov_b64_e32 v[66:67], 0
	v_mov_b64_e32 v[68:69], 0
	v_mov_b64_e32 v[70:71], 0
	v_mov_b64_e32 v[72:73], 0
	v_mov_b64_e32 v[74:75], 0
	v_mov_b64_e32 v[76:77], 0
	v_mov_b64_e32 v[78:79], 0
	v_mov_b64_e32 v[80:81], 0
	v_mov_b64_e32 v[82:83], 0
	v_mov_b64_e32 v[84:85], 0
	v_mov_b64_e32 v[86:87], 0
	v_mov_b64_e32 v[88:89], 0
	v_mov_b64_e32 v[90:91], 0
	v_mov_b64_e32 v[92:93], 0
	v_mov_b64_e32 v[94:95], 0
	v_mov_b64_e32 v[96:97], 0
	v_mov_b64_e32 v[98:99], 0
	v_mov_b64_e32 v[100:101], 0
	v_mov_b64_e32 v[102:103], 0
	v_mov_b64_e32 v[104:105], 0
	v_mov_b64_e32 v[106:107], 0
	v_mov_b64_e32 v[108:109], 0
	v_mov_b64_e32 v[110:111], 0
	v_mov_b64_e32 v[112:113], 0
	v_mov_b64_e32 v[114:115], 0
	v_mov_b64_e32 v[116:117], 0
	v_mov_b64_e32 v[118:119], 0
	v_mov_b64_e32 v[120:121], 0
	v_mov_b64_e32 v[122:123], 0
	v_mov_b64_e32 v[124:125], 0
	v_mov_b64_e32 v[126:127], 0
	v_mov_b64_e32 v[128:129], 0
	.p2align 6

.LBB0_699:
	s_bfe_u32 s9, s74, 0x80008
	s_cmp_lg_u32 s74, 0
	s_cselect_b32 s17, s9, 16
	s_cmp_eq_u32 s17, 0
	.p2align 6
	s_cbranch_scc1 .LBB0_714
	s_add_i32 s19, s17, -2
	s_add_u32 s60, s60, 0x40080
	s_addc_u32 s61, s61, 0
	s_add_u32 s28, s72, 0x100
	v_mov_b32_e32 v2, 0
	s_addc_u32 s29, s73, 0
	s_mov_b32 s26, 0
	v_mov_b64_e32 v[2:3], 0
	v_mov_b64_e32 v[4:5], 0
	v_mov_b64_e32 v[6:7], 0
	v_mov_b64_e32 v[8:9], 0
	v_mov_b64_e32 v[10:11], 0
	v_mov_b64_e32 v[12:13], 0
	v_mov_b64_e32 v[14:15], 0
	v_mov_b64_e32 v[16:17], 0
	v_mov_b64_e32 v[18:19], 0
	v_mov_b64_e32 v[20:21], 0
	v_mov_b64_e32 v[22:23], 0
	v_mov_b64_e32 v[24:25], 0
	v_mov_b64_e32 v[26:27], 0
	v_mov_b64_e32 v[28:29], 0
	v_mov_b64_e32 v[30:31], 0
	v_mov_b64_e32 v[32:33], 0
	v_mov_b64_e32 v[34:35], 0
	v_mov_b64_e32 v[36:37], 0
	v_mov_b64_e32 v[38:39], 0
	v_mov_b64_e32 v[40:41], 0
	v_mov_b64_e32 v[42:43], 0
	v_mov_b64_e32 v[44:45], 0
	v_mov_b64_e32 v[46:47], 0
	v_mov_b64_e32 v[48:49], 0
	v_mov_b64_e32 v[50:51], 0
	v_mov_b64_e32 v[52:53], 0
	v_mov_b64_e32 v[54:55], 0
	v_mov_b64_e32 v[56:57], 0
	v_mov_b64_e32 v[58:59], 0
	v_mov_b64_e32 v[60:61], 0
	v_mov_b64_e32 v[62:63], 0
	v_mov_b64_e32 v[64:65], 0
	v_mov_b64_e32 v[66:67], 0
	v_mov_b64_e32 v[68:69], 0
	v_mov_b64_e32 v[70:71], 0
	v_mov_b64_e32 v[72:73], 0
	v_mov_b64_e32 v[74:75], 0
	v_mov_b64_e32 v[76:77], 0
	v_mov_b64_e32 v[78:79], 0
	v_mov_b64_e32 v[80:81], 0
	v_mov_b64_e32 v[82:83], 0
	v_mov_b64_e32 v[84:85], 0
	v_mov_b64_e32 v[86:87], 0
	v_mov_b64_e32 v[88:89], 0
	v_mov_b64_e32 v[90:91], 0
	v_mov_b64_e32 v[92:93], 0
	v_mov_b64_e32 v[94:95], 0
	v_mov_b64_e32 v[96:97], 0
	v_mov_b64_e32 v[98:99], 0
	v_mov_b64_e32 v[100:101], 0
	v_mov_b64_e32 v[102:103], 0
	v_mov_b64_e32 v[104:105], 0
	v_mov_b64_e32 v[106:107], 0
	v_mov_b64_e32 v[108:109], 0
	v_mov_b64_e32 v[110:111], 0
	v_mov_b64_e32 v[112:113], 0
	v_mov_b64_e32 v[114:115], 0
	v_mov_b64_e32 v[116:117], 0
	v_mov_b64_e32 v[118:119], 0
	v_mov_b64_e32 v[120:121], 0
	v_mov_b64_e32 v[122:123], 0
	v_mov_b64_e32 v[124:125], 0
	v_mov_b64_e32 v[126:127], 0
	v_mov_b64_e32 v[128:129], 0

.LBB0_845:
	s_ashr_i32 s25, s24, 31
	s_lshl_b64 s[26:27], s[24:25], 19
	s_add_u32 s36, s4, s26
	s_addc_u32 s37, s5, s27
	s_and_b64 s[26:27], s[2:3], exec
	s_cselect_b32 s25, s37, s97
	s_cselect_b32 s28, s36, s96
	s_ashr_i32 s23, s22, 31
	s_lshl_b64 s[26:27], s[22:23], 19
	s_add_u32 s26, s41, s26
	s_addc_u32 s27, s42, s27
	s_and_b64 s[78:79], s[2:3], exec
	s_cselect_b32 s23, s27, s39
	s_cselect_b32 s29, s26, s38
	s_add_u32 s96, s96, 0x40080
	s_addc_u32 s97, s97, 0
	s_add_u32 s53, s38, 0x100
	v_mov_b32_e32 v2, 0
	s_addc_u32 s61, s39, 0
	s_mov_b32 s75, -2
	v_mov_b64_e32 v[2:3], 0
	v_mov_b64_e32 v[4:5], 0
	v_mov_b64_e32 v[6:7], 0
	v_mov_b64_e32 v[8:9], 0
	v_mov_b64_e32 v[10:11], 0
	v_mov_b64_e32 v[12:13], 0
	v_mov_b64_e32 v[14:15], 0
	v_mov_b64_e32 v[16:17], 0
	v_mov_b64_e32 v[18:19], 0
	v_mov_b64_e32 v[20:21], 0
	v_mov_b64_e32 v[22:23], 0
	v_mov_b64_e32 v[24:25], 0
	v_mov_b64_e32 v[26:27], 0
	v_mov_b64_e32 v[28:29], 0
	v_mov_b64_e32 v[30:31], 0
	v_mov_b64_e32 v[32:33], 0
	v_mov_b64_e32 v[34:35], 0
	v_mov_b64_e32 v[36:37], 0
	v_mov_b64_e32 v[38:39], 0
	v_mov_b64_e32 v[40:41], 0
	v_mov_b64_e32 v[42:43], 0
	v_mov_b64_e32 v[44:45], 0
	v_mov_b64_e32 v[46:47], 0
	v_mov_b64_e32 v[48:49], 0
	v_mov_b64_e32 v[50:51], 0
	v_mov_b64_e32 v[52:53], 0
	v_mov_b64_e32 v[54:55], 0
	v_mov_b64_e32 v[56:57], 0
	v_mov_b64_e32 v[58:59], 0
	v_mov_b64_e32 v[60:61], 0
	v_mov_b64_e32 v[62:63], 0
	v_mov_b64_e32 v[64:65], 0
	v_mov_b64_e32 v[66:67], 0
	v_mov_b64_e32 v[68:69], 0
	v_mov_b64_e32 v[70:71], 0
	v_mov_b64_e32 v[72:73], 0
	v_mov_b64_e32 v[74:75], 0
	v_mov_b64_e32 v[76:77], 0
	v_mov_b64_e32 v[78:79], 0
	v_mov_b64_e32 v[80:81], 0
	v_mov_b64_e32 v[82:83], 0
	v_mov_b64_e32 v[84:85], 0
	v_mov_b64_e32 v[86:87], 0
	v_mov_b64_e32 v[88:89], 0
	v_mov_b64_e32 v[90:91], 0
	v_mov_b64_e32 v[92:93], 0
	v_mov_b64_e32 v[94:95], 0
	v_mov_b64_e32 v[96:97], 0
	v_mov_b64_e32 v[98:99], 0
	v_mov_b64_e32 v[100:101], 0
	v_mov_b64_e32 v[102:103], 0
	v_mov_b64_e32 v[104:105], 0
	v_mov_b64_e32 v[106:107], 0
	v_mov_b64_e32 v[108:109], 0
	v_mov_b64_e32 v[110:111], 0
	v_mov_b64_e32 v[112:113], 0
	v_mov_b64_e32 v[114:115], 0
	v_mov_b64_e32 v[116:117], 0
	v_mov_b64_e32 v[118:119], 0
	v_mov_b64_e32 v[120:121], 0
	v_mov_b64_e32 v[122:123], 0
	v_mov_b64_e32 v[124:125], 0
	v_mov_b64_e32 v[126:127], 0
	v_mov_b64_e32 v[128:129], 0
	.p2align 6

.LBB0_948:
	s_bfe_u32 s9, s96, 0x80008
	s_cmp_lg_u32 s96, 0
	s_cselect_b32 s28, s9, 44
	s_cmp_eq_u32 s28, 0
	.p2align 6
	s_cbranch_scc1 .LBB0_963
	s_add_i32 s29, s28, -2
	s_add_u32 vcc_lo, s60, 0x100
	v_mov_b32_e32 v2, 0
	s_addc_u32 vcc_hi, s61, 0
	s_mov_b32 s26, 0
	v_mov_b64_e32 v[2:3], 0
	v_mov_b64_e32 v[4:5], 0
	v_mov_b64_e32 v[6:7], 0
	v_mov_b64_e32 v[8:9], 0
	v_mov_b64_e32 v[10:11], 0
	v_mov_b64_e32 v[12:13], 0
	v_mov_b64_e32 v[14:15], 0
	v_mov_b64_e32 v[16:17], 0
	v_mov_b64_e32 v[18:19], 0
	v_mov_b64_e32 v[20:21], 0
	v_mov_b64_e32 v[22:23], 0
	v_mov_b64_e32 v[24:25], 0
	v_mov_b64_e32 v[26:27], 0
	v_mov_b64_e32 v[28:29], 0
	v_mov_b64_e32 v[30:31], 0
	v_mov_b64_e32 v[32:33], 0
	v_mov_b64_e32 v[34:35], 0
	v_mov_b64_e32 v[36:37], 0
	v_mov_b64_e32 v[38:39], 0
	v_mov_b64_e32 v[40:41], 0
	v_mov_b64_e32 v[42:43], 0
	v_mov_b64_e32 v[44:45], 0
	v_mov_b64_e32 v[46:47], 0
	v_mov_b64_e32 v[48:49], 0
	v_mov_b64_e32 v[50:51], 0
	v_mov_b64_e32 v[52:53], 0
	v_mov_b64_e32 v[54:55], 0
	v_mov_b64_e32 v[56:57], 0
	v_mov_b64_e32 v[58:59], 0
	v_mov_b64_e32 v[60:61], 0
	v_mov_b64_e32 v[62:63], 0
	v_mov_b64_e32 v[64:65], 0
	v_mov_b64_e32 v[66:67], 0
	v_mov_b64_e32 v[68:69], 0
	v_mov_b64_e32 v[70:71], 0
	v_mov_b64_e32 v[72:73], 0
	v_mov_b64_e32 v[74:75], 0
	v_mov_b64_e32 v[76:77], 0
	v_mov_b64_e32 v[78:79], 0
	v_mov_b64_e32 v[80:81], 0
	v_mov_b64_e32 v[82:83], 0
	v_mov_b64_e32 v[84:85], 0
	v_mov_b64_e32 v[86:87], 0
	v_mov_b64_e32 v[88:89], 0
	v_mov_b64_e32 v[90:91], 0
	v_mov_b64_e32 v[92:93], 0
	v_mov_b64_e32 v[94:95], 0
	v_mov_b64_e32 v[96:97], 0
	v_mov_b64_e32 v[98:99], 0
	v_mov_b64_e32 v[100:101], 0
	v_mov_b64_e32 v[102:103], 0
	v_mov_b64_e32 v[104:105], 0
	v_mov_b64_e32 v[106:107], 0
	v_mov_b64_e32 v[108:109], 0
	v_mov_b64_e32 v[110:111], 0
	v_mov_b64_e32 v[112:113], 0
	v_mov_b64_e32 v[114:115], 0
	v_mov_b64_e32 v[116:117], 0
	v_mov_b64_e32 v[118:119], 0
	v_mov_b64_e32 v[120:121], 0
	v_mov_b64_e32 v[122:123], 0
	v_mov_b64_e32 v[124:125], 0
	v_mov_b64_e32 v[126:127], 0
	v_mov_b64_e32 v[128:129], 0

.LBB0_1052:
	s_bfe_u32 s9, s74, 0x80008
	s_cmp_lg_u32 s74, 0
	s_cselect_b32 s92, s9, 44
	s_cmp_eq_u32 s92, 0
	.p2align 6
	s_cbranch_scc1 .LBB0_1067
	s_add_i32 s93, s92, -2
	s_add_u32 s94, s36, 0x100
	v_mov_b32_e32 v2, 0
	s_addc_u32 s95, s37, 0
	s_mov_b32 s26, 0
	v_mov_b64_e32 v[2:3], 0
	v_mov_b64_e32 v[4:5], 0
	v_mov_b64_e32 v[6:7], 0
	v_mov_b64_e32 v[8:9], 0
	v_mov_b64_e32 v[10:11], 0
	v_mov_b64_e32 v[12:13], 0
	v_mov_b64_e32 v[14:15], 0
	v_mov_b64_e32 v[16:17], 0
	v_mov_b64_e32 v[18:19], 0
	v_mov_b64_e32 v[20:21], 0
	v_mov_b64_e32 v[22:23], 0
	v_mov_b64_e32 v[24:25], 0
	v_mov_b64_e32 v[26:27], 0
	v_mov_b64_e32 v[28:29], 0
	v_mov_b64_e32 v[30:31], 0
	v_mov_b64_e32 v[32:33], 0
	v_mov_b64_e32 v[34:35], 0
	v_mov_b64_e32 v[36:37], 0
	v_mov_b64_e32 v[38:39], 0
	v_mov_b64_e32 v[40:41], 0
	v_mov_b64_e32 v[42:43], 0
	v_mov_b64_e32 v[44:45], 0
	v_mov_b64_e32 v[46:47], 0
	v_mov_b64_e32 v[48:49], 0
	v_mov_b64_e32 v[50:51], 0
	v_mov_b64_e32 v[52:53], 0
	v_mov_b64_e32 v[54:55], 0
	v_mov_b64_e32 v[56:57], 0
	v_mov_b64_e32 v[58:59], 0
	v_mov_b64_e32 v[60:61], 0
	v_mov_b64_e32 v[62:63], 0
	v_mov_b64_e32 v[64:65], 0
	v_mov_b64_e32 v[66:67], 0
	v_mov_b64_e32 v[68:69], 0
	v_mov_b64_e32 v[70:71], 0
	v_mov_b64_e32 v[72:73], 0
	v_mov_b64_e32 v[74:75], 0
	v_mov_b64_e32 v[76:77], 0
	v_mov_b64_e32 v[78:79], 0
	v_mov_b64_e32 v[80:81], 0
	v_mov_b64_e32 v[82:83], 0
	v_mov_b64_e32 v[84:85], 0
	v_mov_b64_e32 v[86:87], 0
	v_mov_b64_e32 v[88:89], 0
	v_mov_b64_e32 v[90:91], 0
	v_mov_b64_e32 v[92:93], 0
	v_mov_b64_e32 v[94:95], 0
	v_mov_b64_e32 v[96:97], 0
	v_mov_b64_e32 v[98:99], 0
	v_mov_b64_e32 v[100:101], 0
	v_mov_b64_e32 v[102:103], 0
	v_mov_b64_e32 v[104:105], 0
	v_mov_b64_e32 v[106:107], 0
	v_mov_b64_e32 v[108:109], 0
	v_mov_b64_e32 v[110:111], 0
	v_mov_b64_e32 v[112:113], 0
	v_mov_b64_e32 v[114:115], 0
	v_mov_b64_e32 v[116:117], 0
	v_mov_b64_e32 v[118:119], 0
	v_mov_b64_e32 v[120:121], 0
	v_mov_b64_e32 v[122:123], 0
	v_mov_b64_e32 v[124:125], 0
	v_mov_b64_e32 v[126:127], 0
	v_mov_b64_e32 v[128:129], 0
